# NSA: softmax scale folded into q (phase 2 epilogue); selected-block tiles take the running-max offset through the QK MFMA C operand
# speedup vs baseline: 1.0117x; 1.0117x over previous
.Lp2_aq:
	s_mov_b32 s33, s8
	s_lshl_b32 s33, s33, 1
	s_add_u32 s33, s33, s13
	s_lshl_b32 s33, s33, 7
	s_lshl_b32 s34, s6, 10
	s_add_u32 s33, s33, s34
	s_add_u32 s33, s33, 0x4800000
	s_add_u32 s40, s88, s33
	s_addc_u32 s41, s89, 0
	s_movk_i32 s14, 0x400
	s_nop 7
	s_nop 3
	v_mul_f32_e32 v0, 0x3e38aa3b, v0
	v_mul_f32_e32 v1, 0x3e38aa3b, v1
	v_mul_f32_e32 v2, 0x3e38aa3b, v2
	v_mul_f32_e32 v3, 0x3e38aa3b, v3
	v_mul_f32_e32 v4, 0x3e38aa3b, v4
	v_mul_f32_e32 v5, 0x3e38aa3b, v5
	v_mul_f32_e32 v6, 0x3e38aa3b, v6
	v_mul_f32_e32 v7, 0x3e38aa3b, v7
	v_mul_f32_e32 v8, 0x3e38aa3b, v8
	v_mul_f32_e32 v9, 0x3e38aa3b, v9
	v_mul_f32_e32 v10, 0x3e38aa3b, v10
	v_mul_f32_e32 v11, 0x3e38aa3b, v11
	v_mul_f32_e32 v12, 0x3e38aa3b, v12
	v_mul_f32_e32 v13, 0x3e38aa3b, v13
	v_mul_f32_e32 v14, 0x3e38aa3b, v14
	v_mul_f32_e32 v15, 0x3e38aa3b, v15
	v_mul_f32_e32 v16, 0x3e38aa3b, v16
	v_mul_f32_e32 v17, 0x3e38aa3b, v17
	v_mul_f32_e32 v18, 0x3e38aa3b, v18
	v_mul_f32_e32 v19, 0x3e38aa3b, v19
	v_mul_f32_e32 v20, 0x3e38aa3b, v20
	v_mul_f32_e32 v21, 0x3e38aa3b, v21
	v_mul_f32_e32 v22, 0x3e38aa3b, v22
	v_mul_f32_e32 v23, 0x3e38aa3b, v23
	v_mul_f32_e32 v24, 0x3e38aa3b, v24
	v_mul_f32_e32 v25, 0x3e38aa3b, v25
	v_mul_f32_e32 v26, 0x3e38aa3b, v26
	v_mul_f32_e32 v27, 0x3e38aa3b, v27
	v_mul_f32_e32 v28, 0x3e38aa3b, v28
	v_mul_f32_e32 v29, 0x3e38aa3b, v29
	v_mul_f32_e32 v30, 0x3e38aa3b, v30
	v_mul_f32_e32 v31, 0x3e38aa3b, v31
	v_mul_f32_e32 v32, 0x3e38aa3b, v32
	v_mul_f32_e32 v33, 0x3e38aa3b, v33
	v_mul_f32_e32 v34, 0x3e38aa3b, v34
	v_mul_f32_e32 v35, 0x3e38aa3b, v35
	v_mul_f32_e32 v36, 0x3e38aa3b, v36
	v_mul_f32_e32 v37, 0x3e38aa3b, v37
	v_mul_f32_e32 v38, 0x3e38aa3b, v38
	v_mul_f32_e32 v39, 0x3e38aa3b, v39
	v_mul_f32_e32 v40, 0x3e38aa3b, v40
	v_mul_f32_e32 v41, 0x3e38aa3b, v41
	v_mul_f32_e32 v42, 0x3e38aa3b, v42
	v_mul_f32_e32 v43, 0x3e38aa3b, v43
	v_mul_f32_e32 v44, 0x3e38aa3b, v44
	v_mul_f32_e32 v45, 0x3e38aa3b, v45
	v_mul_f32_e32 v46, 0x3e38aa3b, v46
	v_mul_f32_e32 v47, 0x3e38aa3b, v47
	v_mul_f32_e32 v48, 0x3e38aa3b, v48
	v_mul_f32_e32 v49, 0x3e38aa3b, v49
	v_mul_f32_e32 v50, 0x3e38aa3b, v50
	v_mul_f32_e32 v51, 0x3e38aa3b, v51
	v_mul_f32_e32 v52, 0x3e38aa3b, v52
	v_mul_f32_e32 v53, 0x3e38aa3b, v53
	v_mul_f32_e32 v54, 0x3e38aa3b, v54
	v_mul_f32_e32 v55, 0x3e38aa3b, v55
	v_mul_f32_e32 v56, 0x3e38aa3b, v56
	v_mul_f32_e32 v57, 0x3e38aa3b, v57
	v_mul_f32_e32 v58, 0x3e38aa3b, v58
	v_mul_f32_e32 v59, 0x3e38aa3b, v59
	v_mul_f32_e32 v60, 0x3e38aa3b, v60
	v_mul_f32_e32 v61, 0x3e38aa3b, v61
	v_mul_f32_e32 v62, 0x3e38aa3b, v62
	v_mul_f32_e32 v63, 0x3e38aa3b, v63
	s_branch .Lp2_rope

.LBB0_1921:
	v_mul_f32_e32 v2, -1.0, v7
	v_fmamk_f32 v3, v70, 0x3f800000, v2
	v_exp_f32_e32 v3, v3
	v_fmamk_f32 v55, v55, 0x3f800000, v2
	v_exp_f32_e32 v55, v55
	v_fmamk_f32 v54, v54, 0x3f800000, v2
	v_exp_f32_e32 v54, v54
	v_fmamk_f32 v45, v45, 0x3f800000, v2
	v_exp_f32_e32 v45, v45
	v_fmamk_f32 v43, v43, 0x3f800000, v2
	v_add_f32_e32 v3, 0, v3
	v_exp_f32_e32 v43, v43
	v_fmamk_f32 v42, v42, 0x3f800000, v2
	v_add_f32_e32 v3, v55, v3
	v_exp_f32_e32 v42, v42
	v_fmamk_f32 v41, v41, 0x3f800000, v2
	v_add_f32_e32 v3, v54, v3
	v_exp_f32_e32 v41, v41
	v_fmamk_f32 v39, v39, 0x3f800000, v2
	v_add_f32_e32 v3, v45, v3
	v_exp_f32_e32 v39, v39
	v_fmamk_f32 v38, v38, 0x3f800000, v2
	v_add_f32_e32 v3, v43, v3
	v_exp_f32_e32 v38, v38
	v_fmamk_f32 v37, v37, 0x3f800000, v2
	v_add_f32_e32 v3, v42, v3
	v_exp_f32_e32 v37, v37
	v_fmamk_f32 v19, v19, 0x3f800000, v2
	v_add_f32_e32 v3, v41, v3
	v_exp_f32_e32 v19, v19
	v_fmamk_f32 v18, v18, 0x3f800000, v2
	v_add_f32_e32 v3, v39, v3
	v_exp_f32_e32 v18, v18
	v_fmamk_f32 v17, v17, 0x3f800000, v2
	v_add_f32_e32 v3, v38, v3
	v_exp_f32_e32 v17, v17
	v_fmamk_f32 v15, v15, 0x3f800000, v2
	v_add_f32_e32 v3, v37, v3
	v_exp_f32_e32 v15, v15
	v_fmamk_f32 v14, v14, 0x3f800000, v2
	v_add_f32_e32 v3, v19, v3
	v_exp_f32_e32 v14, v14
	v_fmac_f32_e32 v2, 1.0, v10
	v_add_f32_e32 v3, v18, v3
	v_exp_f32_e32 v2, v2
	v_add_f32_e32 v3, v17, v3
	v_add_f32_e32 v3, v15, v3
	v_add_f32_e32 v3, v14, v3
	v_add_f32_e32 v57, v2, v3
	v_mov_b64_e32 v[2:3], v[6:7]
	v_mov_b32_e32 v56, v5

.LBB0_1925:
	v_mov_b32_e32 v6, v186
	s_nop 0
	v_and_b32_e32 v7, 15, v6
	v_bfe_u32 v6, v6, 4, 2
	v_lshlrev_b32_e32 v11, 4, v6
	v_mad_u32_u24 v7, v7, s43, v11
	ds_read_b128 v[54:57], v7
	ds_read_b128 v[58:61], v7 offset:64
	v_lshlrev_b32_e32 v6, 3, v6
	s_waitcnt lgkmcnt(1)
	v_mfma_f32_16x16x32_bf16 v[62:65], v[54:57], v[20:23], 0
	v_sub_u32_e32 v6, v9, v6
	v_cmp_gt_i32_e64 s[0:1], 0, v6
	v_cmp_gt_i32_e64 s[2:3], 1, v6
	v_mfma_f32_16x16x32_bf16 v[54:57], v[54:57], v[28:31], 0
	v_cmp_gt_i32_e64 s[4:5], 2, v6
	v_cmp_gt_i32_e64 s[6:7], 3, v6
	v_cmp_gt_i32_e64 s[8:9], 4, v6
	s_waitcnt lgkmcnt(0)
	v_mfma_f32_16x16x32_bf16 v[62:65], v[58:61], v[24:27], v[62:65]
	v_cmp_gt_i32_e64 s[10:11], 5, v6
	v_cmp_gt_i32_e64 s[14:15], 6, v6
	v_cmp_gt_i32_e64 s[16:17], 7, v6
	v_mfma_f32_16x16x32_bf16 v[54:57], v[58:61], v[32:35], v[54:57]
	ds_read_b128 v[58:61], v7 offset:2304
	ds_read_b128 v[66:69], v7 offset:2368
	ds_read_b128 v[78:81], v7 offset:4608
	ds_read_b128 v[84:87], v7 offset:4672
	ds_read_b128 v[92:95], v7 offset:6912
	ds_read_b128 v[96:99], v7 offset:6976
	s_waitcnt lgkmcnt(5)
	v_mfma_f32_16x16x32_bf16 v[74:77], v[58:61], v[20:23], 0
	v_cndmask_b32_e64 v18, v62, v207, s[0:1]
	v_cndmask_b32_e64 v39, v63, v207, s[2:3]
	v_cndmask_b32_e64 v41, v64, v207, s[4:5]
	v_mfma_f32_16x16x32_bf16 v[58:61], v[58:61], v[28:31], 0
	v_cmp_gt_i32_e64 s[18:19], 32, v6
	v_cmp_gt_i32_e64 s[20:21], 33, v6
	v_cmp_gt_i32_e64 s[22:23], 34, v6
	s_waitcnt lgkmcnt(4)
	v_mfma_f32_16x16x32_bf16 v[88:91], v[66:69], v[24:27], v[74:77]
	v_cmp_gt_i32_e64 s[24:25], 35, v6
	v_cmp_gt_i32_e64 s[26:27], 36, v6
	v_cmp_gt_i32_e64 s[28:29], 37, v6
	v_mfma_f32_16x16x32_bf16 v[58:61], v[66:69], v[32:35], v[58:61]
	v_cndmask_b32_e64 v75, v65, v207, s[6:7]
	v_cmp_gt_i32_e64 s[30:31], 38, v6
	v_cmp_gt_i32_e64 s[34:35], 39, v6
	s_waitcnt lgkmcnt(3)
	v_mfma_f32_16x16x32_bf16 v[66:69], v[78:81], v[20:23], 0
	v_max_f32_e32 v6, v39, v18
	v_mfma_f32_16x16x32_bf16 v[76:79], v[78:81], v[28:31], 0
	v_cndmask_b32_e64 v14, v88, v207, s[8:9]
	v_cndmask_b32_e64 v42, v89, v207, s[10:11]
	v_max3_f32 v6, v6, v41, v75
	s_waitcnt lgkmcnt(2)
	v_mfma_f32_16x16x32_bf16 v[62:65], v[84:87], v[32:35], v[76:79]
	v_cndmask_b32_e64 v43, v90, v207, s[14:15]
	v_cndmask_b32_e64 v71, v91, v207, s[16:17]
	v_max3_f32 v6, v6, v14, v42
	s_waitcnt lgkmcnt(1)
	v_mfma_f32_16x16x32_bf16 v[76:79], v[92:95], v[20:23], 0
	v_max3_f32 v6, v6, v43, v71
	v_mfma_f32_16x16x32_bf16 v[66:69], v[84:87], v[24:27], v[66:69]
	s_waitcnt lgkmcnt(0)
	v_mfma_f32_16x16x32_bf16 v[76:79], v[96:99], v[24:27], v[76:79]
	s_nop 5
	v_cndmask_b32_e64 v15, v66, v207, s[18:19]
	v_cndmask_b32_e64 v45, v67, v207, s[20:21]
	v_cndmask_b32_e64 v19, v68, v207, s[22:23]
	v_cndmask_b32_e64 v74, v69, v207, s[24:25]
	v_mfma_f32_16x16x32_bf16 v[66:69], v[92:95], v[28:31], 0
	v_max3_f32 v6, v6, v15, v45
	v_cndmask_b32_e64 v17, v76, v207, s[26:27]
	v_cndmask_b32_e64 v37, v77, v207, s[28:29]
	v_max3_f32 v6, v6, v19, v74
	v_cndmask_b32_e64 v38, v78, v207, s[30:31]
	v_cndmask_b32_e64 v70, v79, v207, s[34:35]
	v_max3_f32 v6, v6, v17, v37
	v_mfma_f32_16x16x32_bf16 v[66:69], v[96:99], v[32:35], v[66:69]
	v_max3_f32 v6, v6, v38, v70
	v_sub_f32_e32 v7, v6, v2
	v_mul_f32_e32 v7, 1.0, v7
	v_cmp_lt_f32_e32 vcc, s42, v7
	s_cbranch_vccz .LBB0_1930
	v_mov_b32_e32 v7, v6
	s_nop 1
	v_permlane16_swap_b32_e32 v6, v7
	v_max_f32_e32 v6, v7, v6
	v_mov_b32_e32 v7, v6
	s_nop 1
	v_permlane32_swap_b32_e32 v6, v7
	v_max3_f32 v6, v2, v6, v7
	v_mul_f32_e32 v13, -1.0, v6
	v_fmamk_f32 v76, v18, 0x3f800000, v13
	v_exp_f32_e32 v76, v76
	v_fmamk_f32 v77, v39, 0x3f800000, v13
	v_exp_f32_e32 v77, v77
	v_sub_f32_e32 v7, v2, v6
	v_add_f32_e32 v76, 0, v76
	v_mul_f32_e32 v7, 1.0, v7
	v_add_f32_e32 v76, v77, v76
	v_fmamk_f32 v77, v41, 0x3f800000, v13
	v_exp_f32_e32 v77, v77
	v_exp_f32_e32 v11, v7
	v_mov_b32_e32 v7, v3
	v_add_f32_e32 v76, v77, v76
	v_fmamk_f32 v77, v75, 0x3f800000, v13
	v_exp_f32_e32 v77, v77
	v_mul_f32_e32 v11, v10, v11
	v_add_f32_e32 v76, v77, v76
	v_fmamk_f32 v77, v14, 0x3f800000, v13
	v_exp_f32_e32 v77, v77
	s_nop 0
	v_add_f32_e32 v76, v77, v76
	v_fmamk_f32 v77, v42, 0x3f800000, v13
	v_exp_f32_e32 v77, v77
	s_nop 0
	v_add_f32_e32 v76, v77, v76
	v_fmamk_f32 v77, v43, 0x3f800000, v13
	v_exp_f32_e32 v77, v77
	s_nop 0
	v_add_f32_e32 v76, v77, v76
	v_fmamk_f32 v77, v71, 0x3f800000, v13
	v_exp_f32_e32 v77, v77
	s_nop 0
	v_add_f32_e32 v76, v77, v76
	v_fmamk_f32 v77, v15, 0x3f800000, v13
	v_exp_f32_e32 v77, v77
	s_nop 0
	v_add_f32_e32 v76, v77, v76
	v_fmamk_f32 v77, v45, 0x3f800000, v13
	v_exp_f32_e32 v77, v77
	s_nop 0
	v_add_f32_e32 v76, v77, v76
	v_fmamk_f32 v77, v19, 0x3f800000, v13
	v_exp_f32_e32 v77, v77
	s_nop 0
	v_add_f32_e32 v76, v77, v76
	v_fmamk_f32 v77, v74, 0x3f800000, v13
	v_exp_f32_e32 v77, v77
	s_nop 0
	v_add_f32_e32 v76, v77, v76
	v_fmamk_f32 v77, v17, 0x3f800000, v13
	v_exp_f32_e32 v77, v77
	s_nop 0
	v_add_f32_e32 v76, v77, v76
	v_fmamk_f32 v77, v37, 0x3f800000, v13
	v_exp_f32_e32 v77, v77
	s_nop 0
	v_add_f32_e32 v76, v77, v76
	v_fmamk_f32 v77, v38, 0x3f800000, v13
	v_exp_f32_e32 v77, v77
	v_fmac_f32_e32 v13, 1.0, v70
	v_exp_f32_e32 v13, v13
	v_add_f32_e32 v76, v77, v76
	v_add_f32_e32 v13, v13, v76
	s_cbranch_execnz .LBB0_1928
.LBB0_1927:
	v_mul_f32_e32 v6, -1.0, v2
	v_fmamk_f32 v7, v18, 0x3f800000, v6
	v_exp_f32_e32 v7, v7
	v_fmamk_f32 v11, v39, 0x3f800000, v6
	v_exp_f32_e32 v11, v11
	v_fmamk_f32 v13, v41, 0x3f800000, v6
	v_exp_f32_e32 v13, v13
	v_fmamk_f32 v18, v75, 0x3f800000, v6
	v_add_f32_e32 v7, 0, v7
	v_exp_f32_e32 v18, v18
	v_add_f32_e32 v7, v11, v7
	v_fmamk_f32 v11, v14, 0x3f800000, v6
	v_add_f32_e32 v7, v13, v7
	v_exp_f32_e32 v11, v11
	v_fmamk_f32 v13, v42, 0x3f800000, v6
	v_exp_f32_e32 v13, v13
	v_fmamk_f32 v14, v43, 0x3f800000, v6
	v_exp_f32_e32 v14, v14
	v_add_f32_e32 v7, v18, v7
	v_fmamk_f32 v18, v71, 0x3f800000, v6
	v_exp_f32_e32 v18, v18
	v_add_f32_e32 v7, v7, v11
	v_fmamk_f32 v11, v15, 0x3f800000, v6
	v_add_f32_e32 v7, v13, v7
	v_exp_f32_e32 v11, v11
	v_fmamk_f32 v13, v45, 0x3f800000, v6
	v_add_f32_e32 v7, v14, v7
	v_exp_f32_e32 v13, v13
	v_fmamk_f32 v14, v19, 0x3f800000, v6
	v_exp_f32_e32 v14, v14
	v_add_f32_e32 v7, v18, v7
	v_fmamk_f32 v15, v74, 0x3f800000, v6
	v_exp_f32_e32 v15, v15
	v_add_f32_e32 v7, v7, v11
	v_fmamk_f32 v11, v17, 0x3f800000, v6
	v_add_f32_e32 v7, v13, v7
	v_exp_f32_e32 v11, v11
	v_fmamk_f32 v13, v37, 0x3f800000, v6
	v_add_f32_e32 v7, v14, v7
	v_exp_f32_e32 v13, v13
	v_fmamk_f32 v14, v38, 0x3f800000, v6
	v_exp_f32_e32 v14, v14
	v_fmac_f32_e32 v6, 1.0, v70
	v_add_f32_e32 v7, v15, v7
	v_exp_f32_e32 v6, v6
	v_add_f32_e32 v7, v7, v11
	v_add_f32_e32 v7, v13, v7
	v_add_f32_e32 v7, v14, v7
	v_add_f32_e32 v13, v6, v7
	v_mov_b64_e32 v[6:7], v[2:3]
	v_mov_b32_e32 v11, v10
.LBB0_1928:
	v_cndmask_b32_e64 v70, v54, v207, s[0:1]
	v_cndmask_b32_e64 v55, v55, v207, s[2:3]
	v_max_f32_e32 v2, v55, v55
	v_max_f32_e32 v3, v70, v70
	v_cndmask_b32_e64 v54, v56, v207, s[4:5]
	v_cndmask_b32_e64 v45, v57, v207, s[6:7]
	v_max_f32_e32 v2, v3, v2
	v_cndmask_b32_e64 v43, v58, v207, s[8:9]
	v_cndmask_b32_e64 v42, v59, v207, s[10:11]
	v_max3_f32 v2, v2, v54, v45
	v_cndmask_b32_e64 v41, v60, v207, s[14:15]
	v_cndmask_b32_e64 v39, v61, v207, s[16:17]
	v_max3_f32 v2, v2, v43, v42
	v_cndmask_b32_e64 v38, v62, v207, s[18:19]
	v_cndmask_b32_e64 v37, v63, v207, s[20:21]
	v_max3_f32 v2, v2, v41, v39
	v_cndmask_b32_e64 v19, v64, v207, s[22:23]
	v_cndmask_b32_e64 v18, v65, v207, s[24:25]
	v_max3_f32 v2, v2, v38, v37
	v_cndmask_b32_e64 v17, v66, v207, s[26:27]
	v_cndmask_b32_e64 v15, v67, v207, s[28:29]
	v_max3_f32 v2, v2, v19, v18
	v_cndmask_b32_e64 v14, v68, v207, s[30:31]
	v_cndmask_b32_e64 v10, v69, v207, s[34:35]
	v_max3_f32 v2, v2, v17, v15
	v_max3_f32 v2, v2, v14, v10
	v_sub_f32_e32 v3, v2, v7
	v_mul_f32_e32 v3, 1.0, v3
	v_cmp_lt_f32_e32 vcc, s42, v3
	s_cbranch_vccz .LBB0_1931
	v_mov_b32_e32 v3, v2
	s_nop 1
	v_permlane16_swap_b32_e32 v2, v3
	v_max_f32_e32 v2, v3, v2
	v_mov_b32_e32 v3, v2
	s_nop 1
	v_permlane32_swap_b32_e32 v2, v3
	v_max3_f32 v3, v7, v2, v3
	v_mul_f32_e32 v57, -1.0, v3
	v_fmamk_f32 v58, v70, 0x3f800000, v57
	v_exp_f32_e32 v58, v58
	v_fmamk_f32 v59, v55, 0x3f800000, v57
	v_exp_f32_e32 v59, v59
	v_sub_f32_e32 v2, v7, v3
	v_add_f32_e32 v58, 0, v58
	v_mul_f32_e32 v2, 1.0, v2
	v_add_f32_e32 v58, v59, v58
	v_fmamk_f32 v59, v54, 0x3f800000, v57
	v_exp_f32_e32 v59, v59
	v_exp_f32_e32 v56, v2
	v_mov_b32_e32 v2, v6
	v_add_f32_e32 v58, v59, v58
	v_fmamk_f32 v59, v45, 0x3f800000, v57
	v_exp_f32_e32 v59, v59
	v_mul_f32_e32 v56, v5, v56
	v_add_f32_e32 v58, v59, v58
	v_fmamk_f32 v59, v43, 0x3f800000, v57
	v_exp_f32_e32 v59, v59
	s_nop 0
	v_add_f32_e32 v58, v59, v58
	v_fmamk_f32 v59, v42, 0x3f800000, v57
	v_exp_f32_e32 v59, v59
	s_nop 0
	v_add_f32_e32 v58, v59, v58
	v_fmamk_f32 v59, v41, 0x3f800000, v57
	v_exp_f32_e32 v59, v59
	s_nop 0
	v_add_f32_e32 v58, v59, v58
	v_fmamk_f32 v59, v39, 0x3f800000, v57
	v_exp_f32_e32 v59, v59
	s_nop 0
	v_add_f32_e32 v58, v59, v58
	v_fmamk_f32 v59, v38, 0x3f800000, v57
	v_exp_f32_e32 v59, v59
	s_nop 0
	v_add_f32_e32 v58, v59, v58
	v_fmamk_f32 v59, v37, 0x3f800000, v57
	v_exp_f32_e32 v59, v59
	s_nop 0
	v_add_f32_e32 v58, v59, v58
	v_fmamk_f32 v59, v19, 0x3f800000, v57
	v_exp_f32_e32 v59, v59
	s_nop 0
	v_add_f32_e32 v58, v59, v58
	v_fmamk_f32 v59, v18, 0x3f800000, v57
	v_exp_f32_e32 v59, v59
	s_nop 0
	v_add_f32_e32 v58, v59, v58
	v_fmamk_f32 v59, v17, 0x3f800000, v57
	v_exp_f32_e32 v59, v59
	s_nop 0
	v_add_f32_e32 v58, v59, v58
	v_fmamk_f32 v59, v15, 0x3f800000, v57
	v_exp_f32_e32 v59, v59
	s_nop 0
	v_add_f32_e32 v58, v59, v58
	v_fmamk_f32 v59, v14, 0x3f800000, v57
	v_exp_f32_e32 v59, v59
	v_fmac_f32_e32 v57, 1.0, v10
	v_exp_f32_e32 v57, v57
	v_add_f32_e32 v58, v59, v58
	v_add_f32_e32 v57, v57, v58
	s_movk_i32 s34, 0x3fff
	s_cbranch_execnz .LBB0_1922
	s_branch .LBB0_1921

.LBB0_1974:
	v_readlane_b32 s0, v255, 6
	s_add_u32 s12, s0, s33
	v_readlane_b32 s0, v255, 7
	v_mov_b32_e32 v6, v10
	v_mov_b32_e32 v14, v186
	s_addc_u32 s13, s0, 0
	v_readlane_b32 s0, v254, 56
	v_permlane16_swap_b32_e32 v10, v6
	s_add_u32 s0, s0, s39
	v_ashrrev_i32_e32 v15, 31, v14
	v_add_u32_e32 v38, 0x100, v14
	v_readlane_b32 s1, v254, 57
	v_add_f32_e32 v7, v10, v6
	v_lshl_add_u64 v[18:19], v[14:15], 4, s[72:73]
	v_ashrrev_i32_e32 v39, 31, v38
	v_lshlrev_b32_e32 v6, 4, v14
	v_ashrrev_i32_e32 v14, 3, v14
	s_addc_u32 s1, s1, 0
	v_lshl_add_u64 v[42:43], v[38:39], 4, s[72:73]
	global_load_dwordx4 v[48:51], v[18:19], off
	global_load_dwordx4 v[52:55], v[42:43], off
	v_and_b32_e32 v18, 0x70, v6
	v_mov_b32_e32 v19, v161
	v_ashrrev_i32_e32 v15, 31, v14
	v_ashrrev_i32_e32 v38, 3, v38
	v_lshl_add_u64 v[18:19], s[0:1], 0, v[18:19]
	v_lshlrev_b64 v[14:15], 10, v[14:15]
	v_ashrrev_i32_e32 v39, 31, v38
	v_lshl_add_u64 v[14:15], v[18:19], 0, v[14:15]
	v_lshlrev_b64 v[38:39], 10, v[38:39]
	v_lshl_add_u64 v[18:19], v[18:19], 0, v[38:39]
	global_load_dwordx4 v[56:59], v[14:15], off
	global_load_dwordx4 v[60:63], v[18:19], off
	v_mov_b32_e32 v6, v5
	s_nop 1
	v_permlane16_swap_b32_e32 v5, v6
	v_add_f32_e32 v6, v5, v6
	v_mov_b32_e32 v11, v7
	v_mov_b32_e32 v10, v6
	s_nop 0
	v_permlane32_swap_b32_e32 v7, v11
	v_permlane32_swap_b32_e32 v6, v10
	v_pk_add_f32 v[6:7], v[6:7], v[10:11]
	v_lshl_or_b32 v1, v1, 5, v129
	v_div_scale_f32 v5, s[0:1], v7, v7, 1.0
	v_rcp_f32_e32 v9, v5
	v_add_u32_e32 v1, v1, v128
	v_mul_f32_e32 v84, -1.0, v2
	v_mul_f32_e32 v85, -1.0, v3
	v_fma_f32 v10, -v5, v9, 1.0
	v_fmac_f32_e32 v9, v10, v9
	v_div_scale_f32 v10, vcc, 1.0, v7, 1.0
	v_mul_f32_e32 v11, v10, v9
	v_fma_f32 v13, -v5, v11, v10
	v_fmac_f32_e32 v11, v13, v9
	v_fma_f32 v5, -v5, v11, v10
	v_div_fmas_f32 v5, v5, v9, v11
	v_div_scale_f32 v9, s[0:1], v6, v6, 1.0
	v_rcp_f32_e32 v10, v9
	v_div_fixup_f32 v5, v5, v7, 1.0
	v_cmp_lt_f32_e32 vcc, 0, v7
	s_movk_i32 s0, 0x210
	v_mul_lo_u32 v1, v1, s0
	v_cndmask_b32_e32 v74, 0, v5, vcc
	v_fma_f32 v5, -v9, v10, 1.0
	v_fmac_f32_e32 v10, v5, v10
	v_div_scale_f32 v5, vcc, 1.0, v6, 1.0
	v_mul_f32_e32 v7, v5, v10
	v_fma_f32 v11, -v9, v7, v5
	v_fmac_f32_e32 v7, v11, v10
	v_fma_f32 v5, -v9, v7, v5
	v_div_fmas_f32 v5, v5, v10, v7
	v_div_fixup_f32 v5, v5, v6, 1.0
	v_cmp_lt_f32_e32 vcc, 0, v6
	v_mov_b32_e32 v75, v74
	v_add_u32_e32 v86, 0x5800, v1
	v_cndmask_b32_e32 v77, 0, v5, vcc
	v_mov_b32_e32 v78, v77
	v_mov_b32_e32 v80, v77
	v_mov_b32_e32 v81, v77
	s_mov_b32 s33, 0
	v_mov_b32_e32 v45, v44
	s_waitcnt vmcnt(5)
	v_mov_b32_e32 v46, v44
	v_mov_b32_e32 v47, v44
	v_mov_b32_e32 v41, v40
	v_mov_b32_e32 v42, v40
	v_mov_b32_e32 v43, v40
	v_mov_b32_e32 v37, v36
	v_mov_b32_e32 v38, v36
	v_mov_b32_e32 v39, v36
	v_mov_b32_e32 v13, v12
	v_mov_b32_e32 v14, v12
	v_mov_b32_e32 v15, v12
	v_mov_b32_e32 v17, v16
	v_mov_b32_e32 v18, v16
	v_mov_b32_e32 v19, v16
	v_mov_b32_e32 v9, v8
	v_mov_b32_e32 v10, v8
	v_mov_b32_e32 v11, v8
	v_mov_b32_e32 v5, v4
	v_mov_b32_e32 v6, v4
	v_mov_b32_e32 v7, v4
	v_mov_b32_e32 v1, v0
	v_mov_b32_e32 v2, v0
	v_mov_b32_e32 v3, v0
	s_branch .LBB0_1976
.LBB0_1975:
	v_mov_b32_e32 v64, v186
	s_add_u32 s68, s68, 0x2000
	v_bfe_u32 v76, v64, 4, 2
	v_and_b32_e32 v65, 15, v64
	v_lshlrev_b32_e32 v64, 4, v76
	v_mad_u32_u24 v87, v65, s43, v64
	ds_read_b128 v[64:67], v87
	ds_read_b128 v[88:91], v87 offset:64
	ds_read_b128 v[96:99], v87 offset:2368
	ds_read_b128 v[104:107], v87 offset:4672
	ds_read_b128 v[112:115], v87 offset:6976
	v_lshlrev_b32_e32 v116, 3, v76
	s_waitcnt lgkmcnt(4)
	v_mfma_f32_16x16x32_bf16 v[68:71], v[64:67], v[20:23], 0
	s_addc_u32 s69, s69, 0
	s_add_u32 s12, s12, 0x80
	s_addc_u32 s13, s13, 0
	v_mfma_f32_16x16x32_bf16 v[64:67], v[64:67], v[28:31], 0
	s_cmp_eq_u32 s70, s33
	s_waitcnt lgkmcnt(3)
	v_mfma_f32_16x16x32_bf16 v[68:71], v[88:91], v[24:27], v[68:71]
	v_mfma_f32_16x16x32_bf16 v[88:91], v[88:91], v[32:35], v[64:67]
	s_nop 3
	ds_read_b128 v[64:67], v87 offset:2304
	s_waitcnt lgkmcnt(0)
	v_mfma_f32_16x16x32_bf16 v[92:95], v[64:67], v[20:23], 0
	v_mfma_f32_16x16x32_bf16 v[64:67], v[64:67], v[28:31], 0
	v_mfma_f32_16x16x32_bf16 v[92:95], v[96:99], v[24:27], v[92:95]
	v_mfma_f32_16x16x32_bf16 v[96:99], v[96:99], v[32:35], v[64:67]
	s_nop 5
	ds_read_b128 v[64:67], v87 offset:4608
	s_waitcnt lgkmcnt(0)
	v_mfma_f32_16x16x32_bf16 v[100:103], v[64:67], v[20:23], 0
	v_mfma_f32_16x16x32_bf16 v[64:67], v[64:67], v[28:31], 0
	v_mfma_f32_16x16x32_bf16 v[100:103], v[104:107], v[24:27], v[100:103]
	v_mfma_f32_16x16x32_bf16 v[104:107], v[104:107], v[32:35], v[64:67]
	s_nop 5
	ds_read_b128 v[64:67], v87 offset:6912
	s_waitcnt lgkmcnt(0)
	v_mfma_f32_16x16x32_bf16 v[108:111], v[64:67], v[20:23], 0
	v_mfma_f32_16x16x32_bf16 v[64:67], v[64:67], v[28:31], 0
	v_mfma_f32_16x16x32_bf16 v[108:111], v[112:115], v[24:27], v[108:111]
	v_mfma_f32_16x16x32_bf16 v[112:115], v[112:115], v[32:35], v[64:67]
	s_nop 5
	v_sub_u32_e32 v64, v73, v116
	v_cmp_gt_i32_e32 vcc, 0, v64
	v_cmp_gt_i32_e64 s[0:1], 1, v64
	v_cmp_gt_i32_e64 s[2:3], 2, v64
	v_cndmask_b32_e32 v65, v68, v207, vcc
	v_cndmask_b32_e64 v66, v69, v207, s[0:1]
	v_cmp_gt_i32_e64 s[4:5], 3, v64
	v_cmp_gt_i32_e64 s[6:7], 4, v64
	v_cmp_gt_i32_e64 s[8:9], 5, v64
	v_cmp_gt_i32_e64 s[10:11], 6, v64
	v_cmp_gt_i32_e64 s[14:15], 7, v64
	v_cmp_gt_i32_e64 s[16:17], 32, v64
	v_cmp_gt_i32_e64 s[18:19], 33, v64
	v_cmp_gt_i32_e64 s[20:21], 34, v64
	v_cmp_gt_i32_e64 s[22:23], 35, v64
	v_cmp_gt_i32_e64 s[24:25], 36, v64
	v_cmp_gt_i32_e64 s[26:27], 37, v64
	v_cmp_gt_i32_e64 s[28:29], 38, v64
	v_cmp_gt_i32_e64 s[30:31], 39, v64
	v_fmamk_f32 v64, v65, 0x3f800000, v84
	v_cndmask_b32_e64 v67, v70, v207, s[2:3]
	v_cndmask_b32_e64 v119, v101, v207, s[18:19]
	v_exp_f32_e32 v70, v64
	v_fmamk_f32 v64, v66, 0x3f800000, v84
	v_cndmask_b32_e64 v68, v71, v207, s[4:5]
	v_cndmask_b32_e64 v69, v92, v207, s[6:7]
	v_cndmask_b32_e64 v102, v102, v207, s[20:21]
	v_exp_f32_e32 v92, v64
	v_fmamk_f32 v64, v67, 0x3f800000, v84
	v_fmamk_f32 v65, v119, 0x3f800000, v84
	v_cndmask_b32_e64 v79, v94, v207, s[10:11]
	v_cndmask_b32_e64 v103, v103, v207, s[22:23]
	v_exp_f32_e32 v94, v64
	v_fmamk_f32 v64, v68, 0x3f800000, v84
	v_exp_f32_e32 v68, v65
	v_fmamk_f32 v65, v102, 0x3f800000, v84
	v_exp_f32_e32 v66, v65
	v_fmamk_f32 v65, v103, 0x3f800000, v84
	v_exp_f32_e32 v65, v65
	v_cndmask_b32_e32 v88, v88, v207, vcc
	v_cndmask_b32_e64 v89, v89, v207, s[0:1]
	v_fmamk_f32 v88, v88, 0x3f800000, v85
	v_cndmask_b32_e64 v76, v93, v207, s[8:9]
	v_cndmask_b32_e64 v118, v100, v207, s[16:17]
	v_cndmask_b32_e64 v108, v108, v207, s[24:25]
	v_cndmask_b32_e64 v109, v109, v207, s[26:27]
	v_exp_f32_e32 v100, v64
	v_fmamk_f32 v64, v69, 0x3f800000, v84
	v_cndmask_b32_e64 v90, v90, v207, s[2:3]
	v_cndmask_b32_e64 v103, v96, v207, s[6:7]
	v_cndmask_b32_e64 v104, v104, v207, s[16:17]
	v_exp_f32_e32 v96, v88
	v_fmamk_f32 v88, v89, 0x3f800000, v85
	v_cndmask_b32_e64 v111, v111, v207, s[30:31]
	v_exp_f32_e32 v71, v64
	v_fmamk_f32 v64, v76, 0x3f800000, v84
	v_mul_f32_e32 v76, v74, v65
	v_fmamk_f32 v65, v108, 0x3f800000, v84
	v_fmamk_f32 v67, v109, 0x3f800000, v84
	v_cndmask_b32_e64 v108, v97, v207, s[8:9]
	v_cndmask_b32_e64 v109, v98, v207, s[10:11]
	v_cndmask_b32_e64 v105, v105, v207, s[18:19]
	v_exp_f32_e32 v98, v88
	v_fmamk_f32 v88, v90, 0x3f800000, v85
	v_fmamk_f32 v89, v103, 0x3f800000, v85
	v_fmamk_f32 v90, v104, 0x3f800000, v85
	v_cndmask_b32_e64 v117, v95, v207, s[14:15]
	v_cndmask_b32_e64 v110, v110, v207, s[28:29]
	v_exp_f32_e32 v93, v64
	v_fmamk_f32 v64, v79, 0x3f800000, v84
	v_fmamk_f32 v79, v111, 0x3f800000, v84
	v_cndmask_b32_e64 v111, v106, v207, s[20:21]
	v_exp_f32_e32 v97, v89
	v_fmamk_f32 v89, v108, 0x3f800000, v85
	v_exp_f32_e32 v104, v90
	v_fmamk_f32 v90, v105, 0x3f800000, v85
	v_exp_f32_e32 v95, v64
	v_fmamk_f32 v64, v117, 0x3f800000, v84
	v_exp_f32_e32 v69, v67
	v_fmamk_f32 v67, v110, 0x3f800000, v84
	v_cndmask_b32_e64 v91, v91, v207, s[4:5]
	v_cndmask_b32_e64 v110, v99, v207, s[14:15]
	v_cndmask_b32_e64 v107, v107, v207, s[22:23]
	v_exp_f32_e32 v99, v89
	v_fmamk_f32 v89, v109, 0x3f800000, v85
	v_exp_f32_e32 v106, v90
	v_fmamk_f32 v90, v111, 0x3f800000, v85
	v_exp_f32_e32 v101, v64
	v_cndmask_b32_e64 v112, v112, v207, s[24:25]
	v_exp_f32_e32 v102, v88
	v_fmamk_f32 v88, v91, 0x3f800000, v85
	v_exp_f32_e32 v103, v89
	v_fmamk_f32 v89, v110, 0x3f800000, v85
	v_exp_f32_e32 v108, v90
	v_fmamk_f32 v90, v107, 0x3f800000, v85
	v_cndmask_b32_e64 v113, v113, v207, s[26:27]
	v_exp_f32_e32 v88, v88
	v_exp_f32_e32 v89, v89
	v_exp_f32_e32 v110, v90
	v_fmamk_f32 v90, v112, 0x3f800000, v85
	v_cndmask_b32_e64 v114, v114, v207, s[28:29]
	v_exp_f32_e32 v105, v90
	v_fmamk_f32 v90, v113, 0x3f800000, v85
	v_cndmask_b32_e64 v115, v115, v207, s[30:31]
	v_exp_f32_e32 v107, v90
	v_fmamk_f32 v90, v114, 0x3f800000, v85
	v_exp_f32_e32 v109, v90
	v_fmamk_f32 v90, v115, 0x3f800000, v85
	v_pk_mul_f32 v[100:101], v[74:75], v[100:101]
	v_exp_f32_e32 v163, v90
	v_pk_fma_f32 v[90:91], v[100:101], 0.5, 0 op_sel_hi:[1,0,0]
	v_pk_mul_f32 v[112:113], v[80:81], v[88:89]
	v_pk_mul_f32 v[88:89], v[74:75], v[70:71]
	v_pk_fma_f32 v[114:115], v[112:113], 0.5, v[90:91] op_sel_hi:[1,0,1]
	v_pk_mul_f32 v[90:91], v[74:75], v[92:93]
	v_fmamk_f32 v64, v118, 0x3f800000, v84
	v_pk_fma_f32 v[70:71], v[74:75], v[70:71], v[90:91]
	v_add_u32_e32 v118, v86, v116
	v_pk_mul_f32 v[116:117], v[74:75], v[94:95]
	v_pk_fma_f32 v[70:71], v[74:75], v[94:95], v[70:71]
	v_pk_mul_f32 v[94:95], v[80:81], v[98:99]
	v_pk_mul_f32 v[92:93], v[80:81], v[96:97]
	v_pk_fma_f32 v[96:97], v[80:81], v[96:97], v[94:95]
	v_pk_mul_f32 v[98:99], v[80:81], v[102:103]
	v_pk_fma_f32 v[96:97], v[80:81], v[102:103], v[96:97]
	ds_read_b64 v[102:103], v118
	v_pk_fma_f32 v[70:71], v[100:101], 0.5, v[70:71] op_sel_hi:[1,0,1]
	v_pk_fma_f32 v[96:97], v[112:113], 0.5, v[96:97] op_sel_hi:[1,0,1]
	v_pk_add_f32 v[70:71], v[70:71], 0 op_sel_hi:[1,0]
	v_exp_f32_e32 v79, v79
	v_pk_add_f32 v[70:71], v[96:97], v[70:71]
	v_mov_b32_e32 v111, v162
	s_waitcnt lgkmcnt(0)
	v_pk_add_f32 v[70:71], v[70:71], v[102:103]
	ds_write_b64 v118, v[70:71]
	ds_read2_b32 v[70:71], v118 offset0:1 offset1:2
	v_mul_f32_e32 v79, v74, v79
	v_cvt_pk_bf16_f32 v92, v92, v94
	v_cvt_pk_bf16_f32 v94, v93, v95
	v_cvt_pk_bf16_f32 v93, v98, v112
	v_cvt_pk_bf16_f32 v95, v99, v113
	s_waitcnt lgkmcnt(0)
	v_pk_add_f32 v[70:71], v[114:115], v[70:71]
	v_pk_mul_f32 v[98:99], v[78:79], v[110:111]
	v_exp_f32_e32 v64, v64
	v_exp_f32_e32 v65, v65
	v_cvt_pk_bf16_f32 v88, v88, v90
	v_cvt_pk_bf16_f32 v90, v89, v91
	v_cvt_pk_bf16_f32 v89, v116, v100
	v_cvt_pk_bf16_f32 v91, v117, v101
	ds_write2_b32 v118, v70, v71 offset0:1 offset1:2
	v_pk_mul_f32 v[100:101], v[98:99], s[76:77]
	v_pk_fma_f32 v[70:71], v[78:79], v[110:111], s[76:77]
	s_mov_b32 s0, s77
	v_exp_f32_e32 v67, v67
	v_pk_mul_f32 v[96:97], v[76:77], v[162:163]
	v_mov_b32_e32 v101, v71
	v_pk_fma_f32 v[70:71], v[76:77], v[162:163], s[0:1]
	s_mov_b32 s1, s76
	v_pk_mul_f32 v[102:103], v[96:97], s[0:1]
	v_pk_mul_f32 v[68:69], v[74:75], v[68:69]
	v_mov_b32_e32 v71, v103
	v_pk_add_f32 v[110:111], v[70:71], v[100:101]
	v_pk_mul_f32 v[70:71], v[74:75], v[64:65]
	v_pk_fma_f32 v[64:65], v[74:75], v[64:65], v[68:69]
	v_pk_mul_f32 v[112:113], v[74:75], v[66:67]
	v_pk_fma_f32 v[114:115], v[74:75], v[66:67], v[64:65]
	v_cvt_pk_bf16_f32 v64, v70, v68
	v_cvt_pk_bf16_f32 v66, v71, v69
	v_pk_mul_f32 v[70:71], v[80:81], v[106:107]
	v_pk_mul_f32 v[68:69], v[80:81], v[104:105]
	v_pk_fma_f32 v[104:105], v[80:81], v[104:105], v[70:71]
	v_pk_mul_f32 v[106:107], v[80:81], v[108:109]
	v_pk_fma_f32 v[104:105], v[80:81], v[108:109], v[104:105]
	ds_read_b64 v[108:109], v118 offset:32
	v_cvt_pk_bf16_f32 v65, v112, v76
	v_cvt_pk_bf16_f32 v67, v113, v79
	v_mov_b32_e32 v112, v96
	v_mov_b32_e32 v113, v99
	v_pk_add_f32 v[112:113], v[112:113], v[114:115]
	v_mov_b32_e32 v101, v103
	v_pk_add_f32 v[112:113], v[112:113], 0 op_sel_hi:[1,0]
	v_pk_add_f32 v[100:101], v[100:101], v[104:105]
	v_cvt_pk_bf16_f32 v68, v68, v70
	v_pk_add_f32 v[100:101], v[100:101], v[112:113]
	v_cvt_pk_bf16_f32 v70, v69, v71
	v_cvt_pk_bf16_f32 v71, v107, v97
	s_waitcnt lgkmcnt(0)
	v_pk_add_f32 v[96:97], v[100:101], v[108:109]
	ds_write_b64 v118, v[96:97] offset:32
	ds_read2_b32 v[96:97], v118 offset0:9 offset1:10
	v_cvt_pk_bf16_f32 v69, v106, v98
	v_add_u32_e32 v86, 64, v86
	v_subrev_u32_e32 v73, 64, v73
	s_waitcnt lgkmcnt(0)
	v_pk_add_f32 v[96:97], v[110:111], v[96:97]
	ds_write2_b32 v118, v96, v97 offset0:9 offset1:10
	ds_read_b128 v[96:99], v87 offset:13312
	s_waitcnt lgkmcnt(0)
	v_mfma_f32_16x16x32_bf16 v[0:3], v[96:99], v[88:91], v[0:3]
	v_mfma_f32_16x16x32_bf16 v[12:15], v[96:99], v[92:95], v[12:15]
	ds_read_b128 v[96:99], v87 offset:15616
	s_waitcnt lgkmcnt(0)
	v_mfma_f32_16x16x32_bf16 v[4:7], v[96:99], v[88:91], v[4:7]
	v_mfma_f32_16x16x32_bf16 v[36:39], v[96:99], v[92:95], v[36:39]
	ds_read_b128 v[96:99], v87 offset:17920
	s_waitcnt lgkmcnt(0)
	v_mfma_f32_16x16x32_bf16 v[8:11], v[96:99], v[88:91], v[8:11]
	v_mfma_f32_16x16x32_bf16 v[40:43], v[96:99], v[92:95], v[40:43]
	ds_read_b128 v[96:99], v87 offset:20224
	s_waitcnt lgkmcnt(0)
	v_mfma_f32_16x16x32_bf16 v[16:19], v[96:99], v[88:91], v[16:19]
	ds_read_b128 v[88:91], v87 offset:13376
	s_waitcnt lgkmcnt(0)
	v_mfma_f32_16x16x32_bf16 v[0:3], v[88:91], v[64:67], v[0:3]
	v_mfma_f32_16x16x32_bf16 v[12:15], v[88:91], v[68:71], v[12:15]
	ds_read_b128 v[88:91], v87 offset:15680
	s_waitcnt lgkmcnt(0)
	v_mfma_f32_16x16x32_bf16 v[4:7], v[88:91], v[64:67], v[4:7]
	v_mfma_f32_16x16x32_bf16 v[36:39], v[88:91], v[68:71], v[36:39]
	ds_read_b128 v[88:91], v87 offset:17984
	s_waitcnt lgkmcnt(0)
	v_mfma_f32_16x16x32_bf16 v[8:11], v[88:91], v[64:67], v[8:11]
	v_mfma_f32_16x16x32_bf16 v[40:43], v[88:91], v[68:71], v[40:43]
	ds_read_b128 v[88:91], v87 offset:20288
	v_mfma_f32_16x16x32_bf16 v[44:47], v[96:99], v[92:95], v[44:47]
	s_waitcnt lgkmcnt(0)
	v_mfma_f32_16x16x32_bf16 v[16:19], v[88:91], v[64:67], v[16:19]
	v_mfma_f32_16x16x32_bf16 v[44:47], v[88:91], v[68:71], v[44:47]
	s_cbranch_scc1 .LBB0_1978

.LBB0_1990:
	s_lshl_b32 s71, s71, 19
	v_mov_b32_e32 v49, v48
	v_mov_b32_e32 v50, v48
	v_mov_b32_e32 v51, v48
	v_mov_b32_e32 v53, v52
	v_mov_b32_e32 v54, v52
	v_mov_b32_e32 v55, v52
	v_mov_b32_e32 v57, v56
	v_mov_b32_e32 v58, v56
	v_mov_b32_e32 v59, v56
	v_mov_b32_e32 v61, v60
	v_mov_b32_e32 v62, v60
	v_mov_b32_e32 v63, v60
	v_mov_b32_e32 v65, v64
	v_mov_b32_e32 v66, v64
	v_mov_b32_e32 v67, v64
	v_mov_b32_e32 v69, v68
	v_mov_b32_e32 v70, v68
	v_mov_b32_e32 v71, v68
	v_mov_b32_e32 v73, v72
	v_mov_b32_e32 v74, v72
	v_mov_b32_e32 v75, v72
	v_mov_b32_e32 v77, v76
	v_mov_b32_e32 v78, v76
	s_cmp_lt_i32 s2, 0
	v_mov_b32_e32 v79, v76
	s_cbranch_scc1 .LBB0_2008
	s_lshl_b32 s0, s71, 1
	v_readlane_b32 s1, v254, 50
	s_add_u32 s78, s1, s0
	v_readlane_b32 s1, v254, 51
	s_addc_u32 s79, s1, 0
	v_readlane_b32 s1, v254, 44
	s_add_u32 s33, s1, s0
	v_readlane_b32 s0, v254, 45
	s_mov_b32 s3, s77
	s_addc_u32 s39, s0, 0
	s_lshl_b64 s[0:1], s[2:3], 13
	s_add_u32 s0, s78, s0
	v_mov_b32_e32 v92, v186
	s_addc_u32 s1, s79, s1
	s_lshl_b32 s4, s2, 6
	s_mov_b32 s5, s77
	s_lshl_b64 s[4:5], s[4:5], 1
	v_add_u32_e32 v94, 0x100, v92
	v_ashrrev_i32_e32 v93, 31, v92
	v_ashrrev_i32_e32 v95, 31, v94
	s_add_u32 s4, s33, s4
	v_lshl_add_u64 v[84:85], v[92:93], 4, s[0:1]
	v_lshl_add_u64 v[88:89], v[94:95], 4, s[0:1]
	v_lshlrev_b32_e32 v93, 4, v92
	v_ashrrev_i32_e32 v92, 3, v92
	v_ashrrev_i32_e32 v94, 3, v94
	s_addc_u32 s5, s39, s5
	v_and_b32_e32 v160, 0x70, v93
	v_ashrrev_i32_e32 v93, 31, v92
	v_ashrrev_i32_e32 v95, 31, v94
	v_lshl_add_u64 v[96:97], s[4:5], 0, v[160:161]
	v_lshlrev_b64 v[92:93], 14, v[92:93]
	v_lshlrev_b64 v[94:95], 14, v[94:95]
	v_lshl_add_u64 v[92:93], v[96:97], 0, v[92:93]
	v_lshl_add_u64 v[96:97], v[96:97], 0, v[94:95]
	global_load_dwordx4 v[84:87], v[84:85], off
	s_nop 0
	global_load_dwordx4 v[88:91], v[88:89], off
	s_nop 0
	global_load_dwordx4 v[92:95], v[92:93], off
	s_nop 0
	global_load_dwordx4 v[96:99], v[96:97], off
	v_mov_b32_e32 v160, v161
	v_mov_b32_e32 v117, v116
	v_mov_b32_e32 v228, v116
	v_mov_b32_e32 v229, v116
	v_mov_b32_e32 v220, 0
	v_mov_b32_e32 v221, 0
	v_mov_b32_e32 v222, 0
	v_mov_b32_e32 v223, 0
	v_mov_b32_e32 v224, 0
	v_mov_b32_e32 v225, 0
	v_mov_b32_e32 v226, 0
	v_mov_b32_e32 v227, 0
	v_mov_b64_e32 v[118:119], v[160:161]
	s_branch .LBB0_1994

.LBB0_1997:
	s_lshr_b32 s0, s2, 5
	s_cmp_eq_u32 s0, 1
	s_cselect_b64 vcc, -1, 0
	s_cmp_eq_u32 s0, 2
	v_cndmask_b32_e32 v100, v80, v81, vcc
	s_cselect_b64 vcc, -1, 0
	s_cmp_eq_u32 s0, 3
	v_cndmask_b32_e32 v100, v100, v82, vcc
	s_cselect_b64 vcc, -1, 0
	v_cndmask_b32_e32 v100, v100, v83, vcc
	s_and_b32 s3, s2, 31
	v_bfe_u32 v100, v100, s3, 1
	v_cmp_ne_u32_e32 vcc, 0, v100
	s_nop 1
	s_mov_b64 s[0:1], vcc
	s_cbranch_vccz .LBB0_1992
	s_lshl_b32 s2, s2, 6
	ds_read_b128 v[100:103], v245
	ds_read_b128 v[104:107], v245 offset:64
	s_waitcnt lgkmcnt(1)
	v_mfma_f32_16x16x32_bf16 v[108:111], v[100:103], v[20:23], v[220:223]
	v_mfma_f32_16x16x32_bf16 v[100:103], v[100:103], v[28:31], v[224:227]
	s_waitcnt lgkmcnt(0)
	v_mfma_f32_16x16x32_bf16 v[108:111], v[104:107], v[24:27], v[108:111]
	v_mfma_f32_16x16x32_bf16 v[100:103], v[104:107], v[32:35], v[100:103]
	ds_read_b128 v[104:107], v245 offset:2304
	ds_read_b128 v[112:115], v245 offset:2368
	ds_read_b128 v[132:135], v245 offset:4608
	ds_read_b128 v[152:155], v245 offset:4672
	s_waitcnt lgkmcnt(3)
	v_mfma_f32_16x16x32_bf16 v[124:127], v[104:107], v[20:23], v[220:223]
	v_mfma_f32_16x16x32_bf16 v[104:107], v[104:107], v[28:31], v[224:227]
	s_waitcnt lgkmcnt(2)
	v_mfma_f32_16x16x32_bf16 v[138:141], v[112:115], v[24:27], v[124:127]
	s_nop 4
	v_subrev_u32_e32 v124, s2, v120
	v_mfma_f32_16x16x32_bf16 v[104:107], v[112:115], v[32:35], v[104:107]
	ds_read_b128 v[112:115], v245 offset:6912
	ds_read_b128 v[156:159], v245 offset:6976
	v_cndmask_b32_e64 v124, -1, v124, s[0:1]
	v_sub_u32_e32 v136, v124, v248
	s_waitcnt lgkmcnt(3)
	v_mfma_f32_16x16x32_bf16 v[164:167], v[132:135], v[20:23], v[220:223]
	v_cmp_gt_i32_e64 s[0:1], 0, v136
	v_cmp_gt_i32_e64 s[2:3], 1, v136
	v_cmp_gt_i32_e64 s[4:5], 2, v136
	v_mfma_f32_16x16x32_bf16 v[168:171], v[132:135], v[28:31], v[224:227]
	v_cmp_gt_i32_e64 s[6:7], 3, v136
	v_cndmask_b32_e64 v127, v108, v207, s[0:1]
	v_cndmask_b32_e64 v131, v109, v207, s[2:3]
	v_cndmask_b32_e64 v133, v110, v207, s[4:5]
	v_cndmask_b32_e64 v135, v111, v207, s[6:7]
	s_waitcnt lgkmcnt(2)
	v_mfma_f32_16x16x32_bf16 v[164:167], v[152:155], v[24:27], v[164:167]
	v_cmp_gt_i32_e64 s[8:9], 4, v136
	v_cmp_gt_i32_e64 s[10:11], 5, v136
	v_cmp_gt_i32_e64 s[14:15], 6, v136
	v_mfma_f32_16x16x32_bf16 v[108:111], v[152:155], v[32:35], v[168:171]
	v_cmp_gt_i32_e64 s[16:17], 7, v136
	v_cndmask_b32_e64 v137, v138, v207, s[8:9]
	v_cndmask_b32_e64 v138, v139, v207, s[10:11]
	s_waitcnt lgkmcnt(1)
	v_mfma_f32_16x16x32_bf16 v[152:155], v[112:115], v[20:23], v[220:223]
	v_cndmask_b32_e64 v139, v140, v207, s[14:15]
	v_cndmask_b32_e64 v140, v141, v207, s[16:17]
	v_max_f32_e32 v141, v131, v127
	s_waitcnt lgkmcnt(0)
	v_mfma_f32_16x16x32_bf16 v[152:155], v[156:159], v[24:27], v[152:155]
	v_max3_f32 v141, v141, v133, v135
	v_cmp_gt_i32_e64 s[18:19], 32, v136
	v_cmp_gt_i32_e64 s[20:21], 33, v136
	v_max3_f32 v141, v141, v137, v138
	v_cndmask_b32_e64 v123, v164, v207, s[18:19]
	v_cndmask_b32_e64 v124, v165, v207, s[20:21]
	v_mfma_f32_16x16x32_bf16 v[112:115], v[112:115], v[28:31], v[224:227]
	v_cmp_gt_i32_e64 s[22:23], 34, v136
	v_cmp_gt_i32_e64 s[24:25], 35, v136
	v_max3_f32 v141, v141, v139, v140
	v_cndmask_b32_e64 v125, v166, v207, s[22:23]
	v_cndmask_b32_e64 v126, v167, v207, s[24:25]
	v_cmp_gt_i32_e64 s[26:27], 36, v136
	v_cmp_gt_i32_e64 s[28:29], 37, v136
	v_max3_f32 v141, v141, v123, v124
	v_cndmask_b32_e64 v130, v152, v207, s[26:27]
	v_cndmask_b32_e64 v132, v153, v207, s[28:29]
	v_cmp_gt_i32_e64 s[30:31], 38, v136
	v_cmp_gt_i32_e64 s[34:35], 39, v136
	v_max3_f32 v141, v141, v125, v126
	v_cndmask_b32_e64 v134, v154, v207, s[30:31]
	v_cndmask_b32_e64 v136, v155, v207, s[34:35]
	v_max3_f32 v141, v141, v130, v132
	v_mfma_f32_16x16x32_bf16 v[112:115], v[156:159], v[32:35], v[112:115]
	v_max3_f32 v141, v141, v134, v136
	v_sub_f32_e32 v142, v141, v228

	v_cmp_lt_f32_e32 vcc, s42, v142
	s_cbranch_vccz .LBB0_2003
	v_mov_b32_e32 v142, v141
	s_nop 1
	v_permlane16_swap_b32_e32 v141, v142
	v_max_f32_e32 v141, v142, v141
	v_mov_b32_e32 v142, v141
	s_nop 1
	v_permlane32_swap_b32_e32 v141, v142
	v_max3_f32 v142, v228, v141, v142
	v_sub_f32_e32 v116, v228, v142

	v_exp_f32_e32 v116, v116
	v_mov_b32_e32 v143, v117
	v_mul_f32_e32 v118, v118, v116
	v_pk_mul_f32 v[50:51], v[50:51], v[116:117] op_sel_hi:[1,0]
	v_pk_mul_f32 v[48:49], v[48:49], v[116:117] op_sel_hi:[1,0]
	v_pk_mul_f32 v[54:55], v[54:55], v[116:117] op_sel_hi:[1,0]
	v_pk_mul_f32 v[52:53], v[52:53], v[116:117] op_sel_hi:[1,0]
	v_pk_mul_f32 v[58:59], v[58:59], v[116:117] op_sel_hi:[1,0]
	v_pk_mul_f32 v[56:57], v[56:57], v[116:117] op_sel_hi:[1,0]
	v_pk_mul_f32 v[62:63], v[62:63], v[116:117] op_sel_hi:[1,0]
	v_pk_mul_f32 v[60:61], v[60:61], v[116:117] op_sel_hi:[1,0]
	v_mul_f32_e32 v116, -1.0, v142
	v_fmamk_f32 v117, v127, 0x3f800000, v116
	v_exp_f32_e32 v127, v117
	v_fmamk_f32 v117, v131, 0x3f800000, v116
	v_exp_f32_e32 v131, v117
	v_fmamk_f32 v117, v133, 0x3f800000, v116
	v_exp_f32_e32 v133, v117
	v_fmamk_f32 v117, v135, 0x3f800000, v116
	v_exp_f32_e32 v135, v117
	v_fmamk_f32 v137, v137, 0x3f800000, v116
	v_add_f32_e32 v117, 0, v127
	v_exp_f32_e32 v137, v137
	v_fmamk_f32 v138, v138, 0x3f800000, v116
	v_add_f32_e32 v117, v131, v117
	v_exp_f32_e32 v138, v138
	v_fmamk_f32 v139, v139, 0x3f800000, v116
	v_add_f32_e32 v117, v133, v117
	v_exp_f32_e32 v139, v139
	v_fmamk_f32 v140, v140, 0x3f800000, v116
	v_add_f32_e32 v117, v135, v117
	v_exp_f32_e32 v140, v140
	v_fmamk_f32 v123, v123, 0x3f800000, v116
	v_add_f32_e32 v117, v137, v117
	v_exp_f32_e32 v123, v123
	v_fmamk_f32 v124, v124, 0x3f800000, v116
	v_add_f32_e32 v117, v138, v117
	v_exp_f32_e32 v124, v124
	v_fmamk_f32 v125, v125, 0x3f800000, v116
	v_add_f32_e32 v117, v139, v117
	v_exp_f32_e32 v125, v125
	v_fmamk_f32 v126, v126, 0x3f800000, v116
	v_add_f32_e32 v117, v140, v117
	v_exp_f32_e32 v126, v126
	v_fmamk_f32 v130, v130, 0x3f800000, v116
	v_add_f32_e32 v117, v123, v117
	v_exp_f32_e32 v130, v130
	v_fmamk_f32 v132, v132, 0x3f800000, v116
	v_add_f32_e32 v117, v124, v117
	v_exp_f32_e32 v132, v132
	v_fmamk_f32 v134, v134, 0x3f800000, v116
	v_add_f32_e32 v117, v125, v117
	v_exp_f32_e32 v134, v134
	v_fmac_f32_e32 v116, 1.0, v136
	v_add_f32_e32 v117, v126, v117
	v_exp_f32_e32 v136, v116
	v_add_f32_e32 v116, v130, v117
	v_add_f32_e32 v116, v132, v116
	v_add_f32_e32 v116, v134, v116
	v_add_f32_e32 v141, v136, v116
	v_cmp_lt_f32_e32 vcc, 0xec4ecb8f, v142
	v_sub_f32_e32 v230, v142, v220
	s_nop 0
	v_cndmask_b32_e32 v231, 0, v142, vcc
	v_mov_b32_e32 v116, v230
	v_cndmask_b32_e64 v228, v228, 0, vcc
	v_sub_f32_e32 v220, v220, v231
	v_sub_f32_e32 v221, v221, v231
	v_sub_f32_e32 v222, v222, v231
	v_sub_f32_e32 v223, v223, v231
	s_branch .LBB0_2004

.LBB0_2003:
	v_exp_f32_e32 v127, v127
	v_exp_f32_e32 v131, v131
	v_exp_f32_e32 v133, v133
	v_exp_f32_e32 v135, v135
	v_exp_f32_e32 v137, v137
	v_exp_f32_e32 v136, v136
	v_add_f32_e32 v141, 0, v127
	v_exp_f32_e32 v138, v138
	v_add_f32_e32 v141, v131, v141
	v_exp_f32_e32 v139, v139
	v_add_f32_e32 v141, v133, v141
	v_exp_f32_e32 v140, v140
	v_add_f32_e32 v141, v135, v141
	v_exp_f32_e32 v123, v123
	v_add_f32_e32 v141, v141, v137
	v_exp_f32_e32 v124, v124
	v_add_f32_e32 v141, v138, v141
	v_exp_f32_e32 v125, v125
	v_add_f32_e32 v141, v139, v141
	v_exp_f32_e32 v126, v126
	v_add_f32_e32 v141, v140, v141
	v_exp_f32_e32 v130, v130
	v_add_f32_e32 v141, v141, v123
	v_exp_f32_e32 v132, v132
	v_add_f32_e32 v141, v124, v141
	v_exp_f32_e32 v134, v134
	v_add_f32_e32 v141, v125, v141
	v_add_f32_e32 v141, v126, v141
	v_add_f32_e32 v141, v141, v130
	v_add_f32_e32 v141, v132, v141
	v_add_f32_e32 v141, v134, v141
	v_add_f32_e32 v141, v136, v141
.LBB0_2004:
	v_cndmask_b32_e64 v155, v100, v207, s[0:1]
	v_cndmask_b32_e64 v154, v101, v207, s[2:3]
	v_add_f32_e32 v118, v118, v141
	v_cndmask_b32_e64 v143, v105, v207, s[10:11]
	v_cndmask_b32_e64 v141, v107, v207, s[16:17]
	v_max_f32_e32 v105, v154, v154
	v_max_f32_e32 v107, v155, v155
	v_cndmask_b32_e64 v153, v102, v207, s[4:5]
	v_cndmask_b32_e64 v152, v103, v207, s[6:7]
	v_max_f32_e32 v105, v107, v105
	v_cndmask_b32_e64 v151, v104, v207, s[8:9]
	v_max3_f32 v105, v105, v153, v152
	v_cndmask_b32_e64 v142, v106, v207, s[14:15]
	v_max3_f32 v105, v105, v151, v143
	v_cndmask_b32_e64 v101, v108, v207, s[18:19]
	v_cndmask_b32_e64 v102, v109, v207, s[20:21]
	v_max3_f32 v105, v105, v142, v141
	v_cndmask_b32_e64 v103, v110, v207, s[22:23]
	v_cndmask_b32_e64 v104, v111, v207, s[24:25]
	v_max3_f32 v105, v105, v101, v102
	v_cndmask_b32_e64 v106, v112, v207, s[26:27]
	v_cndmask_b32_e64 v108, v113, v207, s[28:29]
	v_max3_f32 v105, v105, v103, v104
	v_cndmask_b32_e64 v110, v114, v207, s[30:31]
	v_cndmask_b32_e64 v100, v115, v207, s[34:35]
	v_max3_f32 v105, v105, v106, v108
	v_max3_f32 v105, v105, v110, v100
	v_sub_f32_e32 v107, v105, v229

	v_cmp_lt_f32_e32 vcc, s42, v107
	s_cbranch_vccz .LBB0_2006
	v_mov_b32_e32 v107, v105
	s_nop 1
	v_permlane16_swap_b32_e32 v105, v107
	v_max_f32_e32 v105, v107, v105
	v_mov_b32_e32 v107, v105
	s_nop 1
	v_permlane32_swap_b32_e32 v105, v107
	v_max3_f32 v105, v229, v105, v107
	v_sub_f32_e32 v107, v229, v105

	v_exp_f32_e32 v112, v107
	v_cmp_lt_f32_e32 vcc, 0xec4ecb8f, v105
	v_sub_f32_e32 v230, v105, v224
	s_nop 0
	v_cndmask_b32_e32 v231, 0, v105, vcc
	v_mov_b32_e32 v117, v230
	v_cndmask_b32_e64 v229, v229, 0, vcc
	v_sub_f32_e32 v224, v224, v231
	v_sub_f32_e32 v225, v225, v231
	v_sub_f32_e32 v226, v226, v231
	v_sub_f32_e32 v227, v227, v231
	v_mul_f32_e32 v119, v119, v112
	v_pk_mul_f32 v[66:67], v[66:67], v[112:113] op_sel_hi:[1,0]
	v_pk_mul_f32 v[64:65], v[64:65], v[112:113] op_sel_hi:[1,0]
	v_pk_mul_f32 v[70:71], v[70:71], v[112:113] op_sel_hi:[1,0]
	v_pk_mul_f32 v[68:69], v[68:69], v[112:113] op_sel_hi:[1,0]
	v_pk_mul_f32 v[74:75], v[74:75], v[112:113] op_sel_hi:[1,0]
	v_pk_mul_f32 v[72:73], v[72:73], v[112:113] op_sel_hi:[1,0]
	v_pk_mul_f32 v[78:79], v[78:79], v[112:113] op_sel_hi:[1,0]
	v_pk_mul_f32 v[76:77], v[76:77], v[112:113] op_sel_hi:[1,0]
	v_mul_f32_e32 v112, -1.0, v105
	v_fmamk_f32 v105, v155, 0x3f800000, v112
	v_exp_f32_e32 v105, v105
	v_fmamk_f32 v107, v154, 0x3f800000, v112
	v_exp_f32_e32 v107, v107
	v_fmamk_f32 v109, v153, 0x3f800000, v112
	v_exp_f32_e32 v109, v109
	v_fmamk_f32 v111, v152, 0x3f800000, v112
	v_exp_f32_e32 v111, v111
	v_add_f32_e32 v113, v107, v105
	v_add_f32_e32 v113, v109, v113
	v_add_f32_e32 v152, v111, v113
	v_fmamk_f32 v113, v151, 0x3f800000, v112
	v_exp_f32_e32 v113, v113
	v_fmamk_f32 v114, v143, 0x3f800000, v112
	v_exp_f32_e32 v114, v114
	v_fmamk_f32 v115, v142, 0x3f800000, v112
	v_exp_f32_e32 v115, v115
	v_fmamk_f32 v141, v141, 0x3f800000, v112
	v_exp_f32_e32 v141, v141
	v_fmamk_f32 v101, v101, 0x3f800000, v112
	v_add_f32_e32 v142, v113, v152
	v_exp_f32_e32 v101, v101
	v_fmamk_f32 v102, v102, 0x3f800000, v112
	v_add_f32_e32 v142, v114, v142
	v_exp_f32_e32 v102, v102
	v_fmamk_f32 v103, v103, 0x3f800000, v112
	v_add_f32_e32 v142, v115, v142
	v_exp_f32_e32 v103, v103
	v_fmamk_f32 v104, v104, 0x3f800000, v112
	v_add_f32_e32 v142, v141, v142
	v_exp_f32_e32 v104, v104
	v_fmamk_f32 v106, v106, 0x3f800000, v112
	v_add_f32_e32 v142, v101, v142
	v_exp_f32_e32 v106, v106
	v_fmamk_f32 v108, v108, 0x3f800000, v112
	v_fmamk_f32 v110, v110, 0x3f800000, v112
	v_fmac_f32_e32 v112, 1.0, v100
	v_add_f32_e32 v142, v102, v142
	v_exp_f32_e32 v108, v108
	v_exp_f32_e32 v110, v110
	v_exp_f32_e32 v112, v112
	v_add_f32_e32 v142, v103, v142
	v_add_f32_e32 v142, v104, v142
	v_add_f32_e32 v100, v106, v142
	s_branch .LBB0_2007
.LBB0_2006:
	v_exp_f32_e32 v105, v155
	v_exp_f32_e32 v107, v154
	v_exp_f32_e32 v109, v153
	v_exp_f32_e32 v111, v152
	v_exp_f32_e32 v113, v151
	v_exp_f32_e32 v112, v100
	v_add_f32_e32 v100, 0, v105
	v_exp_f32_e32 v114, v143
	v_add_f32_e32 v100, v107, v100
	v_exp_f32_e32 v115, v142
	v_add_f32_e32 v100, v109, v100
	v_exp_f32_e32 v141, v141
	v_add_f32_e32 v100, v111, v100
	v_exp_f32_e32 v101, v101
	v_add_f32_e32 v100, v113, v100
	v_exp_f32_e32 v102, v102
	v_add_f32_e32 v100, v114, v100
	v_exp_f32_e32 v103, v103
	v_add_f32_e32 v100, v115, v100
	v_exp_f32_e32 v104, v104
	v_add_f32_e32 v100, v141, v100
	v_exp_f32_e32 v106, v106
	v_add_f32_e32 v100, v101, v100
	v_add_f32_e32 v100, v102, v100
	v_add_f32_e32 v100, v103, v100
	v_add_f32_e32 v100, v104, v100
	v_exp_f32_e32 v108, v108
	v_exp_f32_e32 v110, v110
	v_add_f32_e32 v100, v106, v100

.LBB0_2011:
	v_mov_b32_e32 v135, v133
	s_nop 1
	v_permlane16_swap_b32_e32 v133, v135
	v_max_f32_e32 v133, v135, v133
	v_mov_b32_e32 v135, v133
	s_nop 1
	v_permlane32_swap_b32_e32 v133, v135
	v_max3_f32 v133, v159, v133, v135
	v_sub_f32_e32 v135, v159, v133
	v_mul_f32_e32 v135, 1.0, v135
	v_exp_f32_e32 v140, v135
	v_mov_b32_e32 v159, v133
	v_mul_f32_e32 v153, v153, v140
	v_pk_mul_f32 v[82:83], v[82:83], v[140:141] op_sel_hi:[1,0]
	v_pk_mul_f32 v[80:81], v[80:81], v[140:141] op_sel_hi:[1,0]
	v_pk_mul_f32 v[90:91], v[90:91], v[140:141] op_sel_hi:[1,0]
	v_pk_mul_f32 v[88:89], v[88:89], v[140:141] op_sel_hi:[1,0]
	v_pk_mul_f32 v[106:107], v[106:107], v[140:141] op_sel_hi:[1,0]
	v_pk_mul_f32 v[104:105], v[104:105], v[140:141] op_sel_hi:[1,0]
	v_pk_mul_f32 v[102:103], v[102:103], v[140:141] op_sel_hi:[1,0]
	v_pk_mul_f32 v[100:101], v[100:101], v[140:141] op_sel_hi:[1,0]
	v_mul_f32_e32 v140, -1.0, v133
	v_fmamk_f32 v133, v195, 0x3f800000, v140
	v_exp_f32_e32 v133, v133
	v_fmamk_f32 v135, v192, 0x3f800000, v140
	v_exp_f32_e32 v135, v135
	v_fmamk_f32 v137, v189, 0x3f800000, v140
	v_exp_f32_e32 v137, v137
	v_fmamk_f32 v139, v188, 0x3f800000, v140
	v_exp_f32_e32 v139, v139
	v_add_f32_e32 v141, v135, v133
	v_add_f32_e32 v141, v137, v141
	v_add_f32_e32 v188, v139, v141
	v_fmamk_f32 v141, v185, 0x3f800000, v140
	v_exp_f32_e32 v141, v141
	v_fmamk_f32 v142, v184, 0x3f800000, v140
	v_exp_f32_e32 v142, v142
	v_fmamk_f32 v143, v183, 0x3f800000, v140
	v_exp_f32_e32 v143, v143
	v_fmamk_f32 v182, v182, 0x3f800000, v140
	v_exp_f32_e32 v182, v182
	v_fmamk_f32 v129, v129, 0x3f800000, v140
	v_add_f32_e32 v183, v141, v188
	v_exp_f32_e32 v129, v129
	v_fmamk_f32 v130, v130, 0x3f800000, v140
	v_add_f32_e32 v183, v142, v183
	v_exp_f32_e32 v130, v130
	v_fmamk_f32 v131, v131, 0x3f800000, v140
	v_add_f32_e32 v183, v143, v183
	v_exp_f32_e32 v131, v131
	v_fmamk_f32 v132, v132, 0x3f800000, v140
	v_add_f32_e32 v183, v182, v183
	v_exp_f32_e32 v132, v132
	v_fmamk_f32 v134, v134, 0x3f800000, v140
	v_add_f32_e32 v183, v129, v183
	v_exp_f32_e32 v134, v134
	v_fmamk_f32 v136, v136, 0x3f800000, v140
	v_fmamk_f32 v138, v138, 0x3f800000, v140
	v_fmac_f32_e32 v140, 1.0, v128
	v_add_f32_e32 v183, v130, v183
	v_exp_f32_e32 v136, v136
	v_exp_f32_e32 v138, v138
	v_exp_f32_e32 v140, v140
	v_add_f32_e32 v183, v131, v183
	v_add_f32_e32 v183, v132, v183
	v_add_f32_e32 v128, v134, v183

.LBB0_2015:
	v_mov_b32_e32 v128, v186
	s_nop 0
	v_bfe_u32 v182, v128, 4, 2
	v_and_b32_e32 v165, 15, v128
	v_lshlrev_b32_e32 v160, 4, v182
	v_mad_u32_u24 v178, v165, s43, v160
	ds_read_b128 v[128:131], v178
	ds_read_b128 v[136:139], v178 offset:64
	ds_read_b128 v[140:143], v178 offset:2368
	ds_read_b128 v[174:177], v178 offset:4672
	s_waitcnt lgkmcnt(3)
	v_mfma_f32_16x16x32_bf16 v[132:135], v[128:131], v[20:23], 0
	s_waitcnt lgkmcnt(2)
	v_mfma_f32_16x16x32_bf16 v[166:169], v[136:139], v[24:27], v[132:135]
	s_nop 5
	ds_read_b128 v[132:135], v178 offset:2304
	v_mfma_f32_16x16x32_bf16 v[128:131], v[128:131], v[28:31], 0
	v_mfma_f32_16x16x32_bf16 v[128:131], v[136:139], v[32:35], v[128:131]
	s_waitcnt lgkmcnt(0)
	v_mfma_f32_16x16x32_bf16 v[136:139], v[132:135], v[20:23], 0
	v_mfma_f32_16x16x32_bf16 v[170:173], v[140:143], v[24:27], v[136:139]
	v_mfma_f32_16x16x32_bf16 v[132:135], v[132:135], v[28:31], 0
	s_nop 5
	ds_read_b128 v[136:139], v178 offset:4608
	v_mfma_f32_16x16x32_bf16 v[132:135], v[140:143], v[32:35], v[132:135]
	s_waitcnt lgkmcnt(0)
	v_mfma_f32_16x16x32_bf16 v[140:143], v[136:139], v[20:23], 0
	v_mfma_f32_16x16x32_bf16 v[200:203], v[174:177], v[24:27], v[140:143]
	s_nop 6
	ds_read_b128 v[140:143], v178 offset:6912
	ds_read_b128 v[178:181], v178 offset:6976
	v_mfma_f32_16x16x32_bf16 v[136:139], v[136:139], v[28:31], 0
	v_mfma_f32_16x16x32_bf16 v[136:139], v[174:177], v[32:35], v[136:139]
	s_waitcnt lgkmcnt(1)
	v_mfma_f32_16x16x32_bf16 v[174:177], v[140:143], v[20:23], 0
	v_mfma_f32_16x16x32_bf16 v[140:143], v[140:143], v[28:31], 0
	s_waitcnt lgkmcnt(0)
	v_mfma_f32_16x16x32_bf16 v[174:177], v[178:181], v[24:27], v[174:177]
	v_mfma_f32_16x16x32_bf16 v[140:143], v[178:181], v[32:35], v[140:143]
	v_lshlrev_b32_e32 v178, 3, v182
	v_sub_u32_e32 v188, v164, v178
	v_add_u32_e32 v189, 0x1ff, v188
	v_cmp_gt_i32_e32 vcc, 0, v189
	v_cmp_lt_i32_e64 s[0:1], 0, v188
	s_or_b64 s[0:1], s[0:1], vcc
	v_cmp_gt_i32_e32 vcc, 1, v189
	v_cmp_lt_i32_e64 s[2:3], 1, v188
	s_or_b64 s[2:3], s[2:3], vcc
	v_cmp_gt_i32_e32 vcc, 2, v189
	v_cmp_lt_i32_e64 s[4:5], 2, v188
	s_or_b64 s[4:5], s[4:5], vcc
	v_cmp_gt_i32_e32 vcc, 3, v189
	v_cmp_lt_i32_e64 s[6:7], 3, v188
	s_or_b64 s[6:7], s[6:7], vcc
	v_cmp_gt_i32_e32 vcc, 4, v189
	v_cmp_lt_i32_e64 s[8:9], 4, v188
	s_or_b64 s[8:9], s[8:9], vcc
	v_cmp_gt_i32_e32 vcc, 5, v189
	v_cmp_lt_i32_e64 s[10:11], 5, v188
	s_or_b64 s[10:11], s[10:11], vcc
	v_cmp_gt_i32_e32 vcc, 6, v189
	v_cmp_lt_i32_e64 s[14:15], 6, v188
	s_or_b64 s[14:15], s[14:15], vcc
	v_cmp_gt_i32_e32 vcc, 7, v189
	v_cmp_lt_i32_e64 s[16:17], 7, v188
	s_or_b64 s[16:17], s[16:17], vcc
	v_cmp_gt_i32_e32 vcc, 32, v189
	v_cmp_lt_i32_e64 s[18:19], 32, v188
	v_cndmask_b32_e64 v166, v166, v207, s[0:1]
	v_cndmask_b32_e64 v167, v167, v207, s[2:3]
	s_or_b64 s[18:19], s[18:19], vcc
	v_cmp_gt_i32_e32 vcc, 33, v189
	v_cmp_lt_i32_e64 s[20:21], 33, v188
	v_cndmask_b32_e64 v178, v170, v207, s[8:9]
	v_cndmask_b32_e64 v180, v172, v207, s[14:15]
	s_or_b64 s[20:21], s[20:21], vcc
	v_cmp_gt_i32_e32 vcc, 34, v189
	v_cmp_lt_i32_e64 s[22:23], 34, v188
	v_max_f32_e32 v170, v167, v167
	v_max_f32_e32 v172, v166, v166
	v_cndmask_b32_e64 v168, v168, v207, s[4:5]
	v_cndmask_b32_e64 v169, v169, v207, s[6:7]
	s_or_b64 s[22:23], s[22:23], vcc
	v_cmp_gt_i32_e32 vcc, 35, v189
	v_cmp_lt_i32_e64 s[24:25], 35, v188
	v_max_f32_e32 v170, v172, v170
	v_cndmask_b32_e64 v179, v171, v207, s[10:11]
	s_or_b64 s[24:25], s[24:25], vcc
	v_cmp_gt_i32_e32 vcc, 36, v189
	v_cmp_lt_i32_e64 s[26:27], 36, v188
	v_max3_f32 v170, v170, v168, v169
	v_cndmask_b32_e64 v181, v173, v207, s[16:17]
	s_or_b64 s[26:27], s[26:27], vcc
	v_cmp_gt_i32_e32 vcc, 37, v189
	v_cmp_lt_i32_e64 s[28:29], 37, v188
	v_max3_f32 v170, v170, v178, v179
	v_cndmask_b32_e64 v185, v200, v207, s[18:19]
	v_cndmask_b32_e64 v184, v201, v207, s[20:21]
	s_or_b64 s[28:29], s[28:29], vcc
	v_cmp_gt_i32_e32 vcc, 38, v189
	v_cmp_lt_i32_e64 s[30:31], 38, v188
	v_max3_f32 v170, v170, v180, v181
	v_cndmask_b32_e64 v183, v202, v207, s[22:23]
	v_cndmask_b32_e64 v182, v203, v207, s[24:25]
	s_or_b64 s[30:31], s[30:31], vcc
	v_cmp_gt_i32_e32 vcc, 39, v189
	v_cmp_lt_i32_e64 s[34:35], 39, v188
	v_max3_f32 v170, v170, v185, v184
	v_cndmask_b32_e64 v171, v174, v207, s[26:27]
	v_cndmask_b32_e64 v173, v175, v207, s[28:29]
	s_or_b64 s[34:35], s[34:35], vcc
	v_max3_f32 v170, v170, v183, v182
	v_cndmask_b32_e64 v175, v176, v207, s[30:31]
	v_cndmask_b32_e64 v177, v177, v207, s[34:35]
	v_max3_f32 v170, v170, v171, v173
	v_max3_f32 v170, v170, v175, v177
	v_sub_f32_e32 v172, v170, v158
	v_mul_f32_e32 v172, 1.0, v172
	v_cmp_lt_f32_e32 vcc, s42, v172
	s_cbranch_vccz .LBB0_2017
	v_mov_b32_e32 v172, v170
	s_nop 1
	v_permlane16_swap_b32_e32 v170, v172
	v_max_f32_e32 v170, v172, v170
	v_mov_b32_e32 v172, v170
	s_nop 1
	v_permlane32_swap_b32_e32 v170, v172
	v_max3_f32 v188, v158, v170, v172
	v_sub_f32_e32 v158, v158, v188
	v_mul_f32_e32 v158, 1.0, v158
	v_exp_f32_e32 v158, v158
	v_mov_b32_e32 v189, v159
	v_mul_f32_e32 v152, v152, v158
	v_pk_mul_f32 v[86:87], v[86:87], v[158:159] op_sel_hi:[1,0]
	v_pk_mul_f32 v[84:85], v[84:85], v[158:159] op_sel_hi:[1,0]
	v_pk_mul_f32 v[94:95], v[94:95], v[158:159] op_sel_hi:[1,0]
	v_pk_mul_f32 v[92:93], v[92:93], v[158:159] op_sel_hi:[1,0]
	v_pk_mul_f32 v[98:99], v[98:99], v[158:159] op_sel_hi:[1,0]
	v_pk_mul_f32 v[96:97], v[96:97], v[158:159] op_sel_hi:[1,0]
	v_pk_mul_f32 v[110:111], v[110:111], v[158:159] op_sel_hi:[1,0]
	v_pk_mul_f32 v[108:109], v[108:109], v[158:159] op_sel_hi:[1,0]
	v_mul_f32_e32 v158, -1.0, v188
	v_fmamk_f32 v159, v166, 0x3f800000, v158
	v_exp_f32_e32 v170, v159
	v_fmamk_f32 v159, v167, 0x3f800000, v158
	v_exp_f32_e32 v172, v159
	v_fmamk_f32 v159, v168, 0x3f800000, v158
	v_exp_f32_e32 v174, v159
	v_fmamk_f32 v159, v169, 0x3f800000, v158
	v_exp_f32_e32 v176, v159
	v_fmamk_f32 v166, v178, 0x3f800000, v158
	v_add_f32_e32 v159, 0, v170
	v_exp_f32_e32 v178, v166
	v_fmamk_f32 v166, v179, 0x3f800000, v158
	v_add_f32_e32 v159, v172, v159
	v_exp_f32_e32 v179, v166
	v_fmamk_f32 v166, v180, 0x3f800000, v158
	v_add_f32_e32 v159, v174, v159
	v_exp_f32_e32 v180, v166
	v_fmamk_f32 v166, v181, 0x3f800000, v158
	v_add_f32_e32 v159, v176, v159
	v_exp_f32_e32 v181, v166
	v_fmamk_f32 v166, v185, 0x3f800000, v158
	v_add_f32_e32 v159, v178, v159
	v_exp_f32_e32 v166, v166
	v_fmamk_f32 v167, v184, 0x3f800000, v158
	v_add_f32_e32 v159, v179, v159
	v_exp_f32_e32 v167, v167
	v_fmamk_f32 v168, v183, 0x3f800000, v158
	v_add_f32_e32 v159, v180, v159
	v_exp_f32_e32 v168, v168
	v_fmamk_f32 v169, v182, 0x3f800000, v158
	v_add_f32_e32 v159, v181, v159
	v_exp_f32_e32 v169, v169
	v_fmamk_f32 v171, v171, 0x3f800000, v158
	v_add_f32_e32 v159, v166, v159
	v_exp_f32_e32 v171, v171
	v_fmamk_f32 v173, v173, 0x3f800000, v158
	v_add_f32_e32 v159, v167, v159
	v_exp_f32_e32 v173, v173
	v_fmamk_f32 v175, v175, 0x3f800000, v158
	v_add_f32_e32 v159, v168, v159
	v_exp_f32_e32 v175, v175
	v_fmac_f32_e32 v158, 1.0, v177
	v_add_f32_e32 v159, v169, v159
	v_exp_f32_e32 v177, v158
	v_add_f32_e32 v158, v171, v159
	v_add_f32_e32 v158, v173, v158
	v_add_f32_e32 v158, v175, v158
	v_add_f32_e32 v182, v177, v158
	v_mov_b64_e32 v[158:159], v[188:189]
	s_branch .LBB0_2018
.LBB0_2017:
	v_mul_f32_e32 v188, -1.0, v158
	v_fmamk_f32 v166, v166, 0x3f800000, v188
	v_exp_f32_e32 v170, v166
	v_fmamk_f32 v166, v167, 0x3f800000, v188
	v_exp_f32_e32 v172, v166
	v_fmamk_f32 v166, v168, 0x3f800000, v188
	v_exp_f32_e32 v174, v166
	v_fmamk_f32 v166, v169, 0x3f800000, v188
	v_exp_f32_e32 v176, v166
	v_fmamk_f32 v166, v178, 0x3f800000, v188
	v_exp_f32_e32 v178, v166
	v_fmamk_f32 v166, v179, 0x3f800000, v188
	v_fmamk_f32 v169, v182, 0x3f800000, v188
	v_add_f32_e32 v182, 0, v170
	v_exp_f32_e32 v179, v166
	v_fmamk_f32 v166, v180, 0x3f800000, v188
	v_add_f32_e32 v182, v172, v182
	v_exp_f32_e32 v180, v166
	v_fmamk_f32 v166, v181, 0x3f800000, v188
	v_add_f32_e32 v182, v174, v182
	v_exp_f32_e32 v181, v166
	v_fmamk_f32 v166, v185, 0x3f800000, v188
	v_add_f32_e32 v182, v176, v182
	v_exp_f32_e32 v166, v166
	v_fmamk_f32 v167, v184, 0x3f800000, v188
	v_add_f32_e32 v182, v182, v178
	v_exp_f32_e32 v167, v167
	v_fmamk_f32 v168, v183, 0x3f800000, v188
	v_add_f32_e32 v182, v179, v182
	v_exp_f32_e32 v168, v168
	v_add_f32_e32 v182, v180, v182
	v_exp_f32_e32 v169, v169
	v_fmamk_f32 v171, v171, 0x3f800000, v188
	v_add_f32_e32 v182, v181, v182
	v_exp_f32_e32 v171, v171
	v_fmamk_f32 v173, v173, 0x3f800000, v188
	v_add_f32_e32 v182, v182, v166
	v_exp_f32_e32 v173, v173
	v_fmamk_f32 v175, v175, 0x3f800000, v188
	v_add_f32_e32 v182, v167, v182
	v_exp_f32_e32 v175, v175
	v_fmac_f32_e32 v188, 1.0, v177
	v_add_f32_e32 v182, v168, v182
	v_exp_f32_e32 v177, v188
	v_add_f32_e32 v182, v169, v182
	v_add_f32_e32 v182, v182, v171
	v_add_f32_e32 v182, v173, v182
	v_add_f32_e32 v182, v175, v182
	v_add_f32_e32 v182, v177, v182
.LBB0_2018:
	v_cndmask_b32_e64 v195, v128, v207, s[0:1]
	v_cndmask_b32_e64 v192, v129, v207, s[2:3]
	v_add_f32_e32 v152, v152, v182
	v_cndmask_b32_e64 v184, v133, v207, s[10:11]
	v_cndmask_b32_e64 v182, v135, v207, s[16:17]
	v_max_f32_e32 v133, v192, v192
	v_max_f32_e32 v135, v195, v195
	v_cndmask_b32_e64 v189, v130, v207, s[4:5]
	v_cndmask_b32_e64 v188, v131, v207, s[6:7]
	v_max_f32_e32 v133, v135, v133
	v_cndmask_b32_e64 v185, v132, v207, s[8:9]
	v_max3_f32 v133, v133, v189, v188
	v_cndmask_b32_e64 v183, v134, v207, s[14:15]
	v_max3_f32 v133, v133, v185, v184
	v_cndmask_b32_e64 v129, v136, v207, s[18:19]
	v_cndmask_b32_e64 v130, v137, v207, s[20:21]
	v_max3_f32 v133, v133, v183, v182
	v_cndmask_b32_e64 v131, v138, v207, s[22:23]
	v_cndmask_b32_e64 v132, v139, v207, s[24:25]
	v_max3_f32 v133, v133, v129, v130
	v_cndmask_b32_e64 v134, v140, v207, s[26:27]
	v_cndmask_b32_e64 v136, v141, v207, s[28:29]
	v_max3_f32 v133, v133, v131, v132
	v_cndmask_b32_e64 v138, v142, v207, s[30:31]
	v_cndmask_b32_e64 v128, v143, v207, s[34:35]
	v_max3_f32 v133, v133, v134, v136
	v_max3_f32 v133, v133, v138, v128
	v_sub_f32_e32 v135, v133, v159
	v_mul_f32_e32 v135, 1.0, v135
	v_cmp_lt_f32_e32 vcc, s42, v135
	s_cbranch_vccnz .LBB0_2011
	v_mul_f32_e32 v140, -1.0, v159
	v_fmamk_f32 v133, v195, 0x3f800000, v140
	v_exp_f32_e32 v133, v133
	v_fmamk_f32 v135, v192, 0x3f800000, v140
	v_exp_f32_e32 v135, v135
	v_fmamk_f32 v137, v189, 0x3f800000, v140
	v_exp_f32_e32 v137, v137
	v_fmamk_f32 v139, v188, 0x3f800000, v140
	v_exp_f32_e32 v139, v139
	v_fmamk_f32 v141, v185, 0x3f800000, v140
	v_exp_f32_e32 v141, v141
	v_fmamk_f32 v142, v184, 0x3f800000, v140
	v_fmamk_f32 v143, v183, 0x3f800000, v140
	v_fmamk_f32 v182, v182, 0x3f800000, v140
	v_fmamk_f32 v129, v129, 0x3f800000, v140
	v_fmamk_f32 v130, v130, 0x3f800000, v140
	v_fmamk_f32 v131, v131, 0x3f800000, v140
	v_fmamk_f32 v132, v132, 0x3f800000, v140
	v_fmamk_f32 v134, v134, 0x3f800000, v140
	v_fmamk_f32 v136, v136, 0x3f800000, v140
	v_fmamk_f32 v138, v138, 0x3f800000, v140
	v_fmac_f32_e32 v140, 1.0, v128
	v_add_f32_e32 v128, 0, v133
	v_exp_f32_e32 v142, v142
	v_add_f32_e32 v128, v135, v128
	v_exp_f32_e32 v143, v143
	v_add_f32_e32 v128, v137, v128
	v_exp_f32_e32 v182, v182
	v_add_f32_e32 v128, v139, v128
	v_exp_f32_e32 v129, v129
	v_add_f32_e32 v128, v141, v128
	v_exp_f32_e32 v130, v130
	v_add_f32_e32 v128, v142, v128
	v_exp_f32_e32 v131, v131
	v_add_f32_e32 v128, v143, v128
	v_exp_f32_e32 v132, v132
	v_add_f32_e32 v128, v182, v128
	v_exp_f32_e32 v134, v134
	v_add_f32_e32 v128, v129, v128
	v_add_f32_e32 v128, v130, v128
	v_add_f32_e32 v128, v131, v128
	v_add_f32_e32 v128, v132, v128
	v_exp_f32_e32 v136, v136
	v_exp_f32_e32 v138, v138
	v_exp_f32_e32 v140, v140
	v_add_f32_e32 v128, v134, v128
	s_branch .LBB0_2012
